# attn_prompt: key pairs 1..3 with all keys inside the window take a copy of the loop body without the mask tests and selects
# baseline (speedup 1.0000x reference)
; #define LAS __attribute__((address_space(3)))
; __device__ __forceinline__ void attn_prompt(const Params& p, int j, LAS unsigned char* lds, const int wave, const int lane) {
;     ...
;         for (int kp = kp0; kp < 5; ++kp) {
;             const int kbase = q0 - 144 + 32 * kp, lrow = 16 * wave + 32 * kp;
;             f32x4 st[2];
; #pragma unroll
;             for (int tl = 0; tl < 2; ++tl) {
;                 const LAS unsigned char* kr = Kl + (lrow + tl * 16 + fr) * 144 + g4 * 16;
;                 const bf16x8 kf0 = *(const LAS bf16x8*)kr, kf1 = *(const LAS bf16x8*)(kr + 64);
;                 f32x4 sv = (f32x4){0.f, 0.f, 0.f, 0.f};
;                 sv = __builtin_amdgcn_mfma_f32_16x16x32_bf16(kf0, qf0, sv, 0, 0, 0);
;                 sv = __builtin_amdgcn_mfma_f32_16x16x32_bf16(kf1, qf1, sv, 0, 0, 0);
;                 st[tl] = sv;
;             }
;             float mx = -1e30f; bool val[2][4];
; #pragma unroll
;             for (int tl = 0; tl < 2; ++tl)
; #pragma unroll
;                 for (int e = 0; e < 4; ++e) { const int uk = kbase + tl * 16 + g4 * 4 + e, dist = uq - uk; val[tl][e] = (uk >= 0) && (dist >= 0) && (dist <= 128);
;                     st[tl][e] = val[tl][e] ? st[tl][e] * 0.125f : -1e30f; mx = fmaxf(mx, st[tl][e]); }
;             mx = xmax4(mx);
;             const float mnew = fmaxf(mrun, mx), sc = __expf(mrun - mnew);
;             mrun = mnew; lrun *= sc;
; #pragma unroll
;             for (int dt = 0; dt < 4; ++dt) acc[dt] = acc[dt] * sc;
;             float pv[2][4];
; #pragma unroll
;             for (int tl = 0; tl < 2; ++tl)
; #pragma unroll
;                 for (int e = 0; e < 4; ++e) { pv[tl][e] = val[tl][e] ? __expf(st[tl][e] - mnew) : 0.f; lrun += pv[tl][e]; }
;             bf16x8 pf;
;             { u32x4 w; w.x = pk2(pv[0][0], pv[0][1]); w.y = pk2(pv[0][2], pv[0][3]); w.z = pk2(pv[1][0], pv[1][1]); w.w = pk2(pv[1][2], pv[1][3]); pf = __builtin_bit_cast(bf16x8, w); }
; #pragma unroll
;             for (int dt = 0; dt < 4; ++dt) {
;                 LAS unsigned char* ta = Vl + (lrow + g4 * 4 + (fr >> 2)) * 136 + dt * 32 + 8 * (fr & 3);
;                 const s16x4_ lo = __builtin_amdgcn_ds_read_tr16_b64_v4i16((LAS s16x4_*)ta), hi = __builtin_amdgcn_ds_read_tr16_b64_v4i16((LAS s16x4_*)(ta + 2176));
;                 const bf16x8 vf = (bf16x8){lo[0], lo[1], lo[2], lo[3], hi[0], hi[1], hi[2], hi[3]};
.LBB0_313:
	s_cmp_gt_u32 s25, 2
	s_cbranch_scc1 .Lkp_slow
	s_lshl_b32 s26, s25, 5
	s_add_i32 s26, s26, s24
	s_cmpk_lt_i32 s26, 0x70
	s_cbranch_scc1 .Lkp_slow
	ds_read_b64_tr_b16 v[120:121], v86 offset:39424
	ds_read_b64_tr_b16 v[122:123], v86 offset:41600
	ds_read_b64_tr_b16 v[124:125], v86 offset:39456
	ds_read_b64_tr_b16 v[126:127], v86 offset:41632
	ds_read_b64_tr_b16 v[128:129], v86 offset:39488
	ds_read_b64_tr_b16 v[130:131], v86 offset:41664
	ds_read_b64_tr_b16 v[132:133], v86 offset:39520
	ds_read_b64_tr_b16 v[134:135], v86 offset:41696
	v_mov_b32_e32 v73, v85
	s_waitcnt lgkmcnt(8)
	v_mfma_f32_16x16x32_bf16 v[108:111], v[136:139], v[40:43], 0
	v_mfma_f32_16x16x32_bf16 v[112:115], v[144:147], v[40:43], 0
	v_mfma_f32_16x16x32_bf16 v[108:111], v[140:143], v[44:47], v[108:111]
	v_mfma_f32_16x16x32_bf16 v[112:115], v[148:151], v[44:47], v[112:115]
	ds_read_b128 v[136:139], v84 offset:4608
	ds_read_b128 v[140:143], v84 offset:4672
	ds_read_b128 v[144:147], v84 offset:6912
	ds_read_b128 v[148:151], v84 offset:6976
	s_nop 3
	v_mul_f32_e32 v75, 0x3e000000, v108
	v_mul_f32_e32 v87, 0x3e000000, v109
	v_mul_f32_e32 v108, 0x3e000000, v110
	v_mul_f32_e32 v109, 0x3e000000, v111
	v_mul_f32_e32 v110, 0x3e000000, v112
	v_mul_f32_e32 v111, 0x3e000000, v113
	v_mul_f32_e32 v112, 0x3e000000, v114
	v_mul_f32_e32 v113, 0x3e000000, v115
	s_mov_b32 s26, 0xf149f2ca
	v_max3_f32 v74, v75, s26, v87
	v_max3_f32 v74, v74, v108, v109
	v_max3_f32 v74, v74, v110, v111
	v_max3_f32 v74, v74, v112, v113
	v_mov_b32_e32 v85, v74
	s_nop 1
	v_permlane16_swap_b32 v74, v85
	s_add_i32 s25, s25, 1
	v_max_f32_e32 v85, v85, v85
	v_max_f32_e32 v74, v74, v74
	v_max_f32_e32 v74, v74, v85
	v_mov_b32_e32 v85, v74
	s_nop 1
	v_permlane32_swap_b32 v74, v85
	v_subrev_u32_e32 v81, 32, v81
	v_max3_f32 v85, v73, v74, v85
	v_sub_f32_e32 v73, v73, v85
	v_mul_f32_e32 v73, 0x3fb8aa3b, v73
	v_exp_f32_e32 v74, v73
	v_sub_f32_e32 v73, v75, v85
	v_mul_f32_e32 v73, 0x3fb8aa3b, v73
	v_exp_f32_e32 v73, v73
	v_pk_mul_f32 v[70:71], v[70:71], v[74:75] op_sel_hi:[1,0]
	v_pk_mul_f32 v[68:69], v[68:69], v[74:75] op_sel_hi:[1,0]
	v_pk_mul_f32 v[66:67], v[66:67], v[74:75] op_sel_hi:[1,0]
	v_pk_mul_f32 v[64:65], v[64:65], v[74:75] op_sel_hi:[1,0]
	v_pk_mul_f32 v[62:63], v[62:63], v[74:75] op_sel_hi:[1,0]
	v_pk_mul_f32 v[60:61], v[60:61], v[74:75] op_sel_hi:[1,0]
	v_pk_mul_f32 v[58:59], v[58:59], v[74:75] op_sel_hi:[1,0]
	v_pk_mul_f32 v[56:57], v[56:57], v[74:75] op_sel_hi:[1,0]
	v_fma_f32 v72, v72, v74, v73
	v_sub_f32_e32 v74, v87, v85
	v_mul_f32_e32 v74, 0x3fb8aa3b, v74
	v_sub_f32_e32 v75, v108, v85
	v_exp_f32_e32 v74, v74
	v_mul_f32_e32 v75, 0x3fb8aa3b, v75
	v_sub_f32_e32 v87, v109, v85
	v_exp_f32_e32 v75, v75
	v_mul_f32_e32 v87, 0x3fb8aa3b, v87
	v_sub_f32_e32 v108, v110, v85
	v_exp_f32_e32 v87, v87
	v_mul_f32_e32 v108, 0x3fb8aa3b, v108
	v_sub_f32_e32 v109, v111, v85
	v_exp_f32_e32 v108, v108
	v_mul_f32_e32 v109, 0x3fb8aa3b, v109
	v_sub_f32_e32 v110, v112, v85
	v_exp_f32_e32 v109, v109
	v_mul_f32_e32 v110, 0x3fb8aa3b, v110
	v_add_f32_e32 v72, v74, v72
	v_exp_f32_e32 v110, v110
	v_add_f32_e32 v72, v75, v72
	v_add_f32_e32 v72, v87, v72
	v_add_f32_e32 v72, v108, v72
	v_add_f32_e32 v72, v109, v72
	v_add_f32_e32 v116, v110, v72
	v_sub_f32_e32 v72, v113, v85
	v_mul_f32_e32 v72, 0x3fb8aa3b, v72
	v_exp_f32_e32 v72, v72
	v_add_u32_e32 v83, 32, v83
	v_add_u32_e32 v107, 32, v107
	v_add_u32_e32 v84, 0x1200, v84
	v_mov_b32_e32 v117, v72
	v_cvt_pk_bf16_f32 v72, v73, v74
	v_cvt_pk_bf16_f32 v73, v75, v87
	v_cvt_pk_bf16_f32 v74, v108, v109
	v_cvt_pk_bf16_f32 v75, v110, v117
	v_add_u32_e32 v86, 0x1100, v86
	s_cmp_gt_u32 s25, 3
	s_waitcnt lgkmcnt(4)
	v_mfma_f32_16x16x32_bf16 v[68:71], v[120:123], v[72:75], v[68:71]
	v_mfma_f32_16x16x32_bf16 v[60:63], v[128:131], v[72:75], v[60:63]
	v_mfma_f32_16x16x32_bf16 v[64:67], v[124:127], v[72:75], v[64:67]
	v_mfma_f32_16x16x32_bf16 v[56:59], v[132:135], v[72:75], v[56:59]
	v_add_f32_e32 v72, v117, v116
	s_branch .LBB0_313
